# phase 3 lru conv rewritten: all 19 rows of an item requested up front, fma tap chain
# speedup vs baseline: 1.0032x; 1.0016x over previous
.LBB0_981:
	s_or_b64 exec, exec, s[0:1]
	v_mov_b32_e32 v0, v163
	v_readlane_b32 s0, v250, 4
	s_nop 1
	v_add_u32_e32 v92, s0, v0
	s_mov_b32 s0, 0x42000
	v_cmp_gt_i32_e32 vcc, s0, v92
	s_and_saveexec_b64 s[0:1], vcc
	s_cbranch_execz .LBB0_1024
	v_readlane_b32 s4, v249, 14
	v_readlane_b32 s5, v249, 15
	v_readlane_b32 s6, v249, 12
	v_readlane_b32 s7, v249, 13
	v_readlane_b32 s12, v251, 56
	v_readlane_b32 s13, v251, 57
	v_readlane_b32 s14, v251, 58
	v_readlane_b32 s15, v251, 59
	v_readfirstlane_b32 s2, v92
	v_readlane_b32 s3, v255, 2
	v_and_b32_e32 v181, 0x7f, v92
	v_lshlrev_b32_e32 v180, 5, v181
	v_lshlrev_b32_e32 v181, 4, v181
	s_add_u32 s16, s12, 0x1000
	s_addc_u32 s17, s13, 0
	s_add_u32 s18, s12, 0x2000
	s_addc_u32 s19, s13, 0
	s_add_u32 s20, s12, 0x3000
	s_addc_u32 s21, s13, 0
	global_load_dwordx4 v[76:79], v180, s[12:13] offset:0
	global_load_dwordx4 v[80:83], v180, s[12:13] offset:16
	global_load_dwordx4 v[84:87], v180, s[16:17] offset:0
	global_load_dwordx4 v[88:91], v180, s[16:17] offset:16
	global_load_dwordx4 v[92:95], v180, s[18:19] offset:0
	global_load_dwordx4 v[96:99], v180, s[18:19] offset:16
	global_load_dwordx4 v[100:103], v180, s[20:21] offset:0
	global_load_dwordx4 v[104:107], v180, s[20:21] offset:16
	global_load_dwordx4 v[108:111], v180, s[14:15] offset:0
	global_load_dwordx4 v[112:115], v180, s[14:15] offset:16
.Lp3_item:
	s_lshr_b32 s20, s2, 7
	s_lshl_b32 s20, s20, 4
	s_cmp_lt_u32 s20, 0x8000
	s_cbranch_scc0 .Lp3_ctx
	s_add_u32 s16, s6, 0x4000000
	s_addc_u32 s17, s7, 0
	s_add_u32 s18, s4, 0x4000000
	s_addc_u32 s19, s5, 0
	s_and_b32 s21, s20, 63
	s_mov_b32 s22, 64
	s_branch .Lp3_go
.Lp3_ctx:
	s_sub_u32 s20, s20, 0x8000
	s_add_u32 s16, s4, 0x1C200000
	s_addc_u32 s17, s5, 0
	s_add_u32 s18, s4, 0x1C000000
	s_addc_u32 s19, s5, 0
	s_and_b32 s21, s20, 0xff
	s_mov_b32 s22, 0x100
.Lp3_go:
	s_lshl_b32 s23, s20, 11
	s_add_u32 s16, s16, s23
	s_addc_u32 s17, s17, 0
	s_add_u32 s18, s18, s23
	s_addc_u32 s19, s19, 0
	s_add_u32 s18, s18, 0x1000
	s_addc_u32 s19, s19, 0
	s_add_u32 s25, s21, 16
	s_cmp_eq_u32 s21, 0
	s_cbranch_scc1 .Lp3_lozero
	global_load_dwordx4 v[0:3], v181, s[16:17] offset:-4096 nt
	global_load_dwordx4 v[4:7], v181, s[16:17] offset:-2048 nt
	s_branch .Lp3_lodone
.Lp3_lozero:
	v_mov_b32_e32 v0, 0
	v_mov_b32_e32 v1, 0
	v_mov_b32_e32 v2, 0
	v_mov_b32_e32 v3, 0
	v_mov_b32_e32 v4, 0
	v_mov_b32_e32 v5, 0
	v_mov_b32_e32 v6, 0
	v_mov_b32_e32 v7, 0
.Lp3_lodone:
	global_load_dwordx4 v[8:11], v181, s[16:17] offset:0 nt
	global_load_dwordx4 v[12:15], v181, s[16:17] offset:2048 nt
	s_add_u32 s16, s16, 0x2000
	s_addc_u32 s17, s17, 0
	global_load_dwordx4 v[16:19], v181, s[16:17] offset:-4096 nt
	global_load_dwordx4 v[20:23], v181, s[16:17] offset:-2048 nt
	global_load_dwordx4 v[24:27], v181, s[16:17] offset:0 nt
	global_load_dwordx4 v[28:31], v181, s[16:17] offset:2048 nt
	s_add_u32 s16, s16, 0x2000
	s_addc_u32 s17, s17, 0
	global_load_dwordx4 v[32:35], v181, s[16:17] offset:-4096 nt
	global_load_dwordx4 v[36:39], v181, s[16:17] offset:-2048 nt
	global_load_dwordx4 v[40:43], v181, s[16:17] offset:0 nt
	global_load_dwordx4 v[44:47], v181, s[16:17] offset:2048 nt
	s_add_u32 s16, s16, 0x2000
	s_addc_u32 s17, s17, 0
	global_load_dwordx4 v[48:51], v181, s[16:17] offset:-4096 nt
	global_load_dwordx4 v[52:55], v181, s[16:17] offset:-2048 nt
	global_load_dwordx4 v[56:59], v181, s[16:17] offset:0 nt
	global_load_dwordx4 v[60:63], v181, s[16:17] offset:2048 nt
	s_add_u32 s16, s16, 0x2000
	s_addc_u32 s17, s17, 0
	global_load_dwordx4 v[64:67], v181, s[16:17] offset:-4096 nt
	global_load_dwordx4 v[68:71], v181, s[16:17] offset:-2048 nt
	s_cmp_lt_u32 s25, s22
	s_cselect_b32 s25, 1, 0
	s_cselect_b32 s23, 0, 0x800
	s_sub_u32 s26, s16, s23
	s_subb_u32 s27, s17, 0
	global_load_dwordx4 v[72:75], v181, s[26:27] offset:0 nt
	s_waitcnt vmcnt(16)
	v_lshlrev_b32_e32 v116, 16, v0
	v_and_b32_e32 v117, 0xffff0000, v0
	v_lshlrev_b32_e32 v118, 16, v1
	v_and_b32_e32 v119, 0xffff0000, v1
	v_lshlrev_b32_e32 v120, 16, v2
	v_and_b32_e32 v121, 0xffff0000, v2
	v_lshlrev_b32_e32 v122, 16, v3
	v_and_b32_e32 v123, 0xffff0000, v3
	v_lshlrev_b32_e32 v124, 16, v4
	v_and_b32_e32 v125, 0xffff0000, v4
	v_lshlrev_b32_e32 v126, 16, v5
	v_and_b32_e32 v127, 0xffff0000, v5
	v_lshlrev_b32_e32 v128, 16, v6
	v_and_b32_e32 v129, 0xffff0000, v6
	v_lshlrev_b32_e32 v130, 16, v7
	v_and_b32_e32 v131, 0xffff0000, v7
	v_lshlrev_b32_e32 v132, 16, v8
	v_and_b32_e32 v133, 0xffff0000, v8
	v_lshlrev_b32_e32 v134, 16, v9
	v_and_b32_e32 v135, 0xffff0000, v9
	v_lshlrev_b32_e32 v136, 16, v10
	v_and_b32_e32 v137, 0xffff0000, v10
	v_lshlrev_b32_e32 v138, 16, v11
	v_and_b32_e32 v139, 0xffff0000, v11
	s_waitcnt vmcnt(15)
	v_lshlrev_b32_e32 v140, 16, v12
	v_and_b32_e32 v141, 0xffff0000, v12
	v_lshlrev_b32_e32 v142, 16, v13
	v_and_b32_e32 v143, 0xffff0000, v13
	v_lshlrev_b32_e32 v144, 16, v14
	v_and_b32_e32 v145, 0xffff0000, v14
	v_lshlrev_b32_e32 v146, 16, v15
	v_and_b32_e32 v147, 0xffff0000, v15
	v_pk_fma_f32 v[164:165], v[76:77], v[116:117], v[108:109]
	v_pk_fma_f32 v[166:167], v[78:79], v[118:119], v[110:111]
	v_pk_fma_f32 v[168:169], v[80:81], v[120:121], v[112:113]
	v_pk_fma_f32 v[170:171], v[82:83], v[122:123], v[114:115]
	v_pk_fma_f32 v[164:165], v[84:85], v[124:125], v[164:165]
	v_pk_fma_f32 v[166:167], v[86:87], v[126:127], v[166:167]
	v_pk_fma_f32 v[168:169], v[88:89], v[128:129], v[168:169]
	v_pk_fma_f32 v[170:171], v[90:91], v[130:131], v[170:171]
	v_pk_fma_f32 v[164:165], v[92:93], v[132:133], v[164:165]
	v_pk_fma_f32 v[166:167], v[94:95], v[134:135], v[166:167]
	v_pk_fma_f32 v[168:169], v[96:97], v[136:137], v[168:169]
	v_pk_fma_f32 v[170:171], v[98:99], v[138:139], v[170:171]
	v_pk_fma_f32 v[164:165], v[100:101], v[140:141], v[164:165]
	v_pk_fma_f32 v[166:167], v[102:103], v[142:143], v[166:167]
	v_pk_fma_f32 v[168:169], v[104:105], v[144:145], v[168:169]
	v_pk_fma_f32 v[170:171], v[106:107], v[146:147], v[170:171]
	v_cvt_pk_bf16_f32 v172, v164, v165
	v_cvt_pk_bf16_f32 v173, v166, v167
	v_cvt_pk_bf16_f32 v174, v168, v169
	v_cvt_pk_bf16_f32 v175, v170, v171
	global_store_dwordx4 v181, v[172:175], s[18:19] offset:-4096
	s_waitcnt vmcnt(15)
	v_lshlrev_b32_e32 v116, 16, v16
	v_and_b32_e32 v117, 0xffff0000, v16
	v_lshlrev_b32_e32 v118, 16, v17
	v_and_b32_e32 v119, 0xffff0000, v17
	v_lshlrev_b32_e32 v120, 16, v18
	v_and_b32_e32 v121, 0xffff0000, v18
	v_lshlrev_b32_e32 v122, 16, v19
	v_and_b32_e32 v123, 0xffff0000, v19
	v_pk_fma_f32 v[164:165], v[76:77], v[124:125], v[108:109]
	v_pk_fma_f32 v[166:167], v[78:79], v[126:127], v[110:111]
	v_pk_fma_f32 v[168:169], v[80:81], v[128:129], v[112:113]
	v_pk_fma_f32 v[170:171], v[82:83], v[130:131], v[114:115]
	v_pk_fma_f32 v[164:165], v[84:85], v[132:133], v[164:165]
	v_pk_fma_f32 v[166:167], v[86:87], v[134:135], v[166:167]
	v_pk_fma_f32 v[168:169], v[88:89], v[136:137], v[168:169]
	v_pk_fma_f32 v[170:171], v[90:91], v[138:139], v[170:171]
	v_pk_fma_f32 v[164:165], v[92:93], v[140:141], v[164:165]
	v_pk_fma_f32 v[166:167], v[94:95], v[142:143], v[166:167]
	v_pk_fma_f32 v[168:169], v[96:97], v[144:145], v[168:169]
	v_pk_fma_f32 v[170:171], v[98:99], v[146:147], v[170:171]
	v_pk_fma_f32 v[164:165], v[100:101], v[116:117], v[164:165]
	v_pk_fma_f32 v[166:167], v[102:103], v[118:119], v[166:167]
	v_pk_fma_f32 v[168:169], v[104:105], v[120:121], v[168:169]
	v_pk_fma_f32 v[170:171], v[106:107], v[122:123], v[170:171]
	v_cvt_pk_bf16_f32 v176, v164, v165
	v_cvt_pk_bf16_f32 v177, v166, v167
	v_cvt_pk_bf16_f32 v178, v168, v169
	v_cvt_pk_bf16_f32 v179, v170, v171
	global_store_dwordx4 v181, v[176:179], s[18:19] offset:-2048
	s_waitcnt vmcnt(15)
	v_lshlrev_b32_e32 v124, 16, v20
	v_and_b32_e32 v125, 0xffff0000, v20
	v_lshlrev_b32_e32 v126, 16, v21
	v_and_b32_e32 v127, 0xffff0000, v21
	v_lshlrev_b32_e32 v128, 16, v22
	v_and_b32_e32 v129, 0xffff0000, v22
	v_lshlrev_b32_e32 v130, 16, v23
	v_and_b32_e32 v131, 0xffff0000, v23
	v_pk_fma_f32 v[164:165], v[76:77], v[132:133], v[108:109]
	v_pk_fma_f32 v[166:167], v[78:79], v[134:135], v[110:111]
	v_pk_fma_f32 v[168:169], v[80:81], v[136:137], v[112:113]
	v_pk_fma_f32 v[170:171], v[82:83], v[138:139], v[114:115]
	v_pk_fma_f32 v[164:165], v[84:85], v[140:141], v[164:165]
	v_pk_fma_f32 v[166:167], v[86:87], v[142:143], v[166:167]
	v_pk_fma_f32 v[168:169], v[88:89], v[144:145], v[168:169]
	v_pk_fma_f32 v[170:171], v[90:91], v[146:147], v[170:171]
	v_pk_fma_f32 v[164:165], v[92:93], v[116:117], v[164:165]
	v_pk_fma_f32 v[166:167], v[94:95], v[118:119], v[166:167]
	v_pk_fma_f32 v[168:169], v[96:97], v[120:121], v[168:169]
	v_pk_fma_f32 v[170:171], v[98:99], v[122:123], v[170:171]
	v_pk_fma_f32 v[164:165], v[100:101], v[124:125], v[164:165]
	v_pk_fma_f32 v[166:167], v[102:103], v[126:127], v[166:167]
	v_pk_fma_f32 v[168:169], v[104:105], v[128:129], v[168:169]
	v_pk_fma_f32 v[170:171], v[106:107], v[130:131], v[170:171]
	v_cvt_pk_bf16_f32 v172, v164, v165
	v_cvt_pk_bf16_f32 v173, v166, v167
	v_cvt_pk_bf16_f32 v174, v168, v169
	v_cvt_pk_bf16_f32 v175, v170, v171
	global_store_dwordx4 v181, v[172:175], s[18:19] offset:0
	s_waitcnt vmcnt(15)
	v_lshlrev_b32_e32 v132, 16, v24
	v_and_b32_e32 v133, 0xffff0000, v24
	v_lshlrev_b32_e32 v134, 16, v25
	v_and_b32_e32 v135, 0xffff0000, v25
	v_lshlrev_b32_e32 v136, 16, v26
	v_and_b32_e32 v137, 0xffff0000, v26
	v_lshlrev_b32_e32 v138, 16, v27
	v_and_b32_e32 v139, 0xffff0000, v27
	v_pk_fma_f32 v[164:165], v[76:77], v[140:141], v[108:109]
	v_pk_fma_f32 v[166:167], v[78:79], v[142:143], v[110:111]
	v_pk_fma_f32 v[168:169], v[80:81], v[144:145], v[112:113]
	v_pk_fma_f32 v[170:171], v[82:83], v[146:147], v[114:115]
	v_pk_fma_f32 v[164:165], v[84:85], v[116:117], v[164:165]
	v_pk_fma_f32 v[166:167], v[86:87], v[118:119], v[166:167]
	v_pk_fma_f32 v[168:169], v[88:89], v[120:121], v[168:169]
	v_pk_fma_f32 v[170:171], v[90:91], v[122:123], v[170:171]
	v_pk_fma_f32 v[164:165], v[92:93], v[124:125], v[164:165]
	v_pk_fma_f32 v[166:167], v[94:95], v[126:127], v[166:167]
	v_pk_fma_f32 v[168:169], v[96:97], v[128:129], v[168:169]
	v_pk_fma_f32 v[170:171], v[98:99], v[130:131], v[170:171]
	v_pk_fma_f32 v[164:165], v[100:101], v[132:133], v[164:165]
	v_pk_fma_f32 v[166:167], v[102:103], v[134:135], v[166:167]
	v_pk_fma_f32 v[168:169], v[104:105], v[136:137], v[168:169]
	v_pk_fma_f32 v[170:171], v[106:107], v[138:139], v[170:171]
	v_cvt_pk_bf16_f32 v176, v164, v165
	v_cvt_pk_bf16_f32 v177, v166, v167
	v_cvt_pk_bf16_f32 v178, v168, v169
	v_cvt_pk_bf16_f32 v179, v170, v171
	global_store_dwordx4 v181, v[176:179], s[18:19] offset:2048
	s_waitcnt vmcnt(15)
	v_lshlrev_b32_e32 v140, 16, v28
	v_and_b32_e32 v141, 0xffff0000, v28
	v_lshlrev_b32_e32 v142, 16, v29
	v_and_b32_e32 v143, 0xffff0000, v29
	v_lshlrev_b32_e32 v144, 16, v30
	v_and_b32_e32 v145, 0xffff0000, v30
	v_lshlrev_b32_e32 v146, 16, v31
	v_and_b32_e32 v147, 0xffff0000, v31
	v_pk_fma_f32 v[164:165], v[76:77], v[116:117], v[108:109]
	v_pk_fma_f32 v[166:167], v[78:79], v[118:119], v[110:111]
	v_pk_fma_f32 v[168:169], v[80:81], v[120:121], v[112:113]
	v_pk_fma_f32 v[170:171], v[82:83], v[122:123], v[114:115]
	v_pk_fma_f32 v[164:165], v[84:85], v[124:125], v[164:165]
	v_pk_fma_f32 v[166:167], v[86:87], v[126:127], v[166:167]
	v_pk_fma_f32 v[168:169], v[88:89], v[128:129], v[168:169]
	v_pk_fma_f32 v[170:171], v[90:91], v[130:131], v[170:171]
	v_pk_fma_f32 v[164:165], v[92:93], v[132:133], v[164:165]
	v_pk_fma_f32 v[166:167], v[94:95], v[134:135], v[166:167]
	v_pk_fma_f32 v[168:169], v[96:97], v[136:137], v[168:169]
	v_pk_fma_f32 v[170:171], v[98:99], v[138:139], v[170:171]
	v_pk_fma_f32 v[164:165], v[100:101], v[140:141], v[164:165]
	v_pk_fma_f32 v[166:167], v[102:103], v[142:143], v[166:167]
	v_pk_fma_f32 v[168:169], v[104:105], v[144:145], v[168:169]
	v_pk_fma_f32 v[170:171], v[106:107], v[146:147], v[170:171]
	v_cvt_pk_bf16_f32 v172, v164, v165
	v_cvt_pk_bf16_f32 v173, v166, v167
	v_cvt_pk_bf16_f32 v174, v168, v169
	v_cvt_pk_bf16_f32 v175, v170, v171
	s_add_u32 s18, s18, 0x2000
	s_addc_u32 s19, s19, 0
	global_store_dwordx4 v181, v[172:175], s[18:19] offset:-4096
	s_waitcnt vmcnt(15)
	v_lshlrev_b32_e32 v116, 16, v32
	v_and_b32_e32 v117, 0xffff0000, v32
	v_lshlrev_b32_e32 v118, 16, v33
	v_and_b32_e32 v119, 0xffff0000, v33
	v_lshlrev_b32_e32 v120, 16, v34
	v_and_b32_e32 v121, 0xffff0000, v34
	v_lshlrev_b32_e32 v122, 16, v35
	v_and_b32_e32 v123, 0xffff0000, v35
	v_pk_fma_f32 v[164:165], v[76:77], v[124:125], v[108:109]
	v_pk_fma_f32 v[166:167], v[78:79], v[126:127], v[110:111]
	v_pk_fma_f32 v[168:169], v[80:81], v[128:129], v[112:113]
	v_pk_fma_f32 v[170:171], v[82:83], v[130:131], v[114:115]
	v_pk_fma_f32 v[164:165], v[84:85], v[132:133], v[164:165]
	v_pk_fma_f32 v[166:167], v[86:87], v[134:135], v[166:167]
	v_pk_fma_f32 v[168:169], v[88:89], v[136:137], v[168:169]
	v_pk_fma_f32 v[170:171], v[90:91], v[138:139], v[170:171]
	v_pk_fma_f32 v[164:165], v[92:93], v[140:141], v[164:165]
	v_pk_fma_f32 v[166:167], v[94:95], v[142:143], v[166:167]
	v_pk_fma_f32 v[168:169], v[96:97], v[144:145], v[168:169]
	v_pk_fma_f32 v[170:171], v[98:99], v[146:147], v[170:171]
	v_pk_fma_f32 v[164:165], v[100:101], v[116:117], v[164:165]
	v_pk_fma_f32 v[166:167], v[102:103], v[118:119], v[166:167]
	v_pk_fma_f32 v[168:169], v[104:105], v[120:121], v[168:169]
	v_pk_fma_f32 v[170:171], v[106:107], v[122:123], v[170:171]
	v_cvt_pk_bf16_f32 v176, v164, v165
	v_cvt_pk_bf16_f32 v177, v166, v167
	v_cvt_pk_bf16_f32 v178, v168, v169
	v_cvt_pk_bf16_f32 v179, v170, v171
	global_store_dwordx4 v181, v[176:179], s[18:19] offset:-2048
	s_waitcnt vmcnt(15)
	v_lshlrev_b32_e32 v124, 16, v36
	v_and_b32_e32 v125, 0xffff0000, v36
	v_lshlrev_b32_e32 v126, 16, v37
	v_and_b32_e32 v127, 0xffff0000, v37
	v_lshlrev_b32_e32 v128, 16, v38
	v_and_b32_e32 v129, 0xffff0000, v38
	v_lshlrev_b32_e32 v130, 16, v39
	v_and_b32_e32 v131, 0xffff0000, v39
	v_pk_fma_f32 v[164:165], v[76:77], v[132:133], v[108:109]
	v_pk_fma_f32 v[166:167], v[78:79], v[134:135], v[110:111]
	v_pk_fma_f32 v[168:169], v[80:81], v[136:137], v[112:113]
	v_pk_fma_f32 v[170:171], v[82:83], v[138:139], v[114:115]
	v_pk_fma_f32 v[164:165], v[84:85], v[140:141], v[164:165]
	v_pk_fma_f32 v[166:167], v[86:87], v[142:143], v[166:167]
	v_pk_fma_f32 v[168:169], v[88:89], v[144:145], v[168:169]
	v_pk_fma_f32 v[170:171], v[90:91], v[146:147], v[170:171]
	v_pk_fma_f32 v[164:165], v[92:93], v[116:117], v[164:165]
	v_pk_fma_f32 v[166:167], v[94:95], v[118:119], v[166:167]
	v_pk_fma_f32 v[168:169], v[96:97], v[120:121], v[168:169]
	v_pk_fma_f32 v[170:171], v[98:99], v[122:123], v[170:171]
	v_pk_fma_f32 v[164:165], v[100:101], v[124:125], v[164:165]
	v_pk_fma_f32 v[166:167], v[102:103], v[126:127], v[166:167]
	v_pk_fma_f32 v[168:169], v[104:105], v[128:129], v[168:169]
	v_pk_fma_f32 v[170:171], v[106:107], v[130:131], v[170:171]
	v_cvt_pk_bf16_f32 v172, v164, v165
	v_cvt_pk_bf16_f32 v173, v166, v167
	v_cvt_pk_bf16_f32 v174, v168, v169
	v_cvt_pk_bf16_f32 v175, v170, v171
	global_store_dwordx4 v181, v[172:175], s[18:19] offset:0
	s_waitcnt vmcnt(15)
	v_lshlrev_b32_e32 v132, 16, v40
	v_and_b32_e32 v133, 0xffff0000, v40
	v_lshlrev_b32_e32 v134, 16, v41
	v_and_b32_e32 v135, 0xffff0000, v41
	v_lshlrev_b32_e32 v136, 16, v42
	v_and_b32_e32 v137, 0xffff0000, v42
	v_lshlrev_b32_e32 v138, 16, v43
	v_and_b32_e32 v139, 0xffff0000, v43
	v_pk_fma_f32 v[164:165], v[76:77], v[140:141], v[108:109]
	v_pk_fma_f32 v[166:167], v[78:79], v[142:143], v[110:111]
	v_pk_fma_f32 v[168:169], v[80:81], v[144:145], v[112:113]
	v_pk_fma_f32 v[170:171], v[82:83], v[146:147], v[114:115]
	v_pk_fma_f32 v[164:165], v[84:85], v[116:117], v[164:165]
	v_pk_fma_f32 v[166:167], v[86:87], v[118:119], v[166:167]
	v_pk_fma_f32 v[168:169], v[88:89], v[120:121], v[168:169]
	v_pk_fma_f32 v[170:171], v[90:91], v[122:123], v[170:171]
	v_pk_fma_f32 v[164:165], v[92:93], v[124:125], v[164:165]
	v_pk_fma_f32 v[166:167], v[94:95], v[126:127], v[166:167]
	v_pk_fma_f32 v[168:169], v[96:97], v[128:129], v[168:169]
	v_pk_fma_f32 v[170:171], v[98:99], v[130:131], v[170:171]
	v_pk_fma_f32 v[164:165], v[100:101], v[132:133], v[164:165]
	v_pk_fma_f32 v[166:167], v[102:103], v[134:135], v[166:167]
	v_pk_fma_f32 v[168:169], v[104:105], v[136:137], v[168:169]
	v_pk_fma_f32 v[170:171], v[106:107], v[138:139], v[170:171]
	v_cvt_pk_bf16_f32 v176, v164, v165
	v_cvt_pk_bf16_f32 v177, v166, v167
	v_cvt_pk_bf16_f32 v178, v168, v169
	v_cvt_pk_bf16_f32 v179, v170, v171
	global_store_dwordx4 v181, v[176:179], s[18:19] offset:2048
	s_waitcnt vmcnt(15)
	v_lshlrev_b32_e32 v140, 16, v44
	v_and_b32_e32 v141, 0xffff0000, v44
	v_lshlrev_b32_e32 v142, 16, v45
	v_and_b32_e32 v143, 0xffff0000, v45
	v_lshlrev_b32_e32 v144, 16, v46
	v_and_b32_e32 v145, 0xffff0000, v46
	v_lshlrev_b32_e32 v146, 16, v47
	v_and_b32_e32 v147, 0xffff0000, v47
	v_pk_fma_f32 v[164:165], v[76:77], v[116:117], v[108:109]
	v_pk_fma_f32 v[166:167], v[78:79], v[118:119], v[110:111]
	v_pk_fma_f32 v[168:169], v[80:81], v[120:121], v[112:113]
	v_pk_fma_f32 v[170:171], v[82:83], v[122:123], v[114:115]
	v_pk_fma_f32 v[164:165], v[84:85], v[124:125], v[164:165]
	v_pk_fma_f32 v[166:167], v[86:87], v[126:127], v[166:167]
	v_pk_fma_f32 v[168:169], v[88:89], v[128:129], v[168:169]
	v_pk_fma_f32 v[170:171], v[90:91], v[130:131], v[170:171]
	v_pk_fma_f32 v[164:165], v[92:93], v[132:133], v[164:165]
	v_pk_fma_f32 v[166:167], v[94:95], v[134:135], v[166:167]
	v_pk_fma_f32 v[168:169], v[96:97], v[136:137], v[168:169]
	v_pk_fma_f32 v[170:171], v[98:99], v[138:139], v[170:171]
	v_pk_fma_f32 v[164:165], v[100:101], v[140:141], v[164:165]
	v_pk_fma_f32 v[166:167], v[102:103], v[142:143], v[166:167]
	v_pk_fma_f32 v[168:169], v[104:105], v[144:145], v[168:169]
	v_pk_fma_f32 v[170:171], v[106:107], v[146:147], v[170:171]
	v_cvt_pk_bf16_f32 v172, v164, v165
	v_cvt_pk_bf16_f32 v173, v166, v167
	v_cvt_pk_bf16_f32 v174, v168, v169
	v_cvt_pk_bf16_f32 v175, v170, v171
	s_add_u32 s18, s18, 0x2000
	s_addc_u32 s19, s19, 0
	global_store_dwordx4 v181, v[172:175], s[18:19] offset:-4096
	s_waitcnt vmcnt(15)
	v_lshlrev_b32_e32 v116, 16, v48
	v_and_b32_e32 v117, 0xffff0000, v48
	v_lshlrev_b32_e32 v118, 16, v49
	v_and_b32_e32 v119, 0xffff0000, v49
	v_lshlrev_b32_e32 v120, 16, v50
	v_and_b32_e32 v121, 0xffff0000, v50
	v_lshlrev_b32_e32 v122, 16, v51
	v_and_b32_e32 v123, 0xffff0000, v51
	v_pk_fma_f32 v[164:165], v[76:77], v[124:125], v[108:109]
	v_pk_fma_f32 v[166:167], v[78:79], v[126:127], v[110:111]
	v_pk_fma_f32 v[168:169], v[80:81], v[128:129], v[112:113]
	v_pk_fma_f32 v[170:171], v[82:83], v[130:131], v[114:115]
	v_pk_fma_f32 v[164:165], v[84:85], v[132:133], v[164:165]
	v_pk_fma_f32 v[166:167], v[86:87], v[134:135], v[166:167]
	v_pk_fma_f32 v[168:169], v[88:89], v[136:137], v[168:169]
	v_pk_fma_f32 v[170:171], v[90:91], v[138:139], v[170:171]
	v_pk_fma_f32 v[164:165], v[92:93], v[140:141], v[164:165]
	v_pk_fma_f32 v[166:167], v[94:95], v[142:143], v[166:167]
	v_pk_fma_f32 v[168:169], v[96:97], v[144:145], v[168:169]
	v_pk_fma_f32 v[170:171], v[98:99], v[146:147], v[170:171]
	v_pk_fma_f32 v[164:165], v[100:101], v[116:117], v[164:165]
	v_pk_fma_f32 v[166:167], v[102:103], v[118:119], v[166:167]
	v_pk_fma_f32 v[168:169], v[104:105], v[120:121], v[168:169]
	v_pk_fma_f32 v[170:171], v[106:107], v[122:123], v[170:171]
	v_cvt_pk_bf16_f32 v176, v164, v165
	v_cvt_pk_bf16_f32 v177, v166, v167
	v_cvt_pk_bf16_f32 v178, v168, v169
	v_cvt_pk_bf16_f32 v179, v170, v171
	global_store_dwordx4 v181, v[176:179], s[18:19] offset:-2048
	s_waitcnt vmcnt(15)
	v_lshlrev_b32_e32 v124, 16, v52
	v_and_b32_e32 v125, 0xffff0000, v52
	v_lshlrev_b32_e32 v126, 16, v53
	v_and_b32_e32 v127, 0xffff0000, v53
	v_lshlrev_b32_e32 v128, 16, v54
	v_and_b32_e32 v129, 0xffff0000, v54
	v_lshlrev_b32_e32 v130, 16, v55
	v_and_b32_e32 v131, 0xffff0000, v55
	v_pk_fma_f32 v[164:165], v[76:77], v[132:133], v[108:109]
	v_pk_fma_f32 v[166:167], v[78:79], v[134:135], v[110:111]
	v_pk_fma_f32 v[168:169], v[80:81], v[136:137], v[112:113]
	v_pk_fma_f32 v[170:171], v[82:83], v[138:139], v[114:115]
	v_pk_fma_f32 v[164:165], v[84:85], v[140:141], v[164:165]
	v_pk_fma_f32 v[166:167], v[86:87], v[142:143], v[166:167]
	v_pk_fma_f32 v[168:169], v[88:89], v[144:145], v[168:169]
	v_pk_fma_f32 v[170:171], v[90:91], v[146:147], v[170:171]
	v_pk_fma_f32 v[164:165], v[92:93], v[116:117], v[164:165]
	v_pk_fma_f32 v[166:167], v[94:95], v[118:119], v[166:167]
	v_pk_fma_f32 v[168:169], v[96:97], v[120:121], v[168:169]
	v_pk_fma_f32 v[170:171], v[98:99], v[122:123], v[170:171]
	v_pk_fma_f32 v[164:165], v[100:101], v[124:125], v[164:165]
	v_pk_fma_f32 v[166:167], v[102:103], v[126:127], v[166:167]
	v_pk_fma_f32 v[168:169], v[104:105], v[128:129], v[168:169]
	v_pk_fma_f32 v[170:171], v[106:107], v[130:131], v[170:171]
	v_cvt_pk_bf16_f32 v172, v164, v165
	v_cvt_pk_bf16_f32 v173, v166, v167
	v_cvt_pk_bf16_f32 v174, v168, v169
	v_cvt_pk_bf16_f32 v175, v170, v171
	global_store_dwordx4 v181, v[172:175], s[18:19] offset:0
	s_waitcnt vmcnt(15)
	v_lshlrev_b32_e32 v132, 16, v56
	v_and_b32_e32 v133, 0xffff0000, v56
	v_lshlrev_b32_e32 v134, 16, v57
	v_and_b32_e32 v135, 0xffff0000, v57
	v_lshlrev_b32_e32 v136, 16, v58
	v_and_b32_e32 v137, 0xffff0000, v58
	v_lshlrev_b32_e32 v138, 16, v59
	v_and_b32_e32 v139, 0xffff0000, v59
	v_pk_fma_f32 v[164:165], v[76:77], v[140:141], v[108:109]
	v_pk_fma_f32 v[166:167], v[78:79], v[142:143], v[110:111]
	v_pk_fma_f32 v[168:169], v[80:81], v[144:145], v[112:113]
	v_pk_fma_f32 v[170:171], v[82:83], v[146:147], v[114:115]
	v_pk_fma_f32 v[164:165], v[84:85], v[116:117], v[164:165]
	v_pk_fma_f32 v[166:167], v[86:87], v[118:119], v[166:167]
	v_pk_fma_f32 v[168:169], v[88:89], v[120:121], v[168:169]
	v_pk_fma_f32 v[170:171], v[90:91], v[122:123], v[170:171]
	v_pk_fma_f32 v[164:165], v[92:93], v[124:125], v[164:165]
	v_pk_fma_f32 v[166:167], v[94:95], v[126:127], v[166:167]
	v_pk_fma_f32 v[168:169], v[96:97], v[128:129], v[168:169]
	v_pk_fma_f32 v[170:171], v[98:99], v[130:131], v[170:171]
	v_pk_fma_f32 v[164:165], v[100:101], v[132:133], v[164:165]
	v_pk_fma_f32 v[166:167], v[102:103], v[134:135], v[166:167]
	v_pk_fma_f32 v[168:169], v[104:105], v[136:137], v[168:169]
	v_pk_fma_f32 v[170:171], v[106:107], v[138:139], v[170:171]
	v_cvt_pk_bf16_f32 v176, v164, v165
	v_cvt_pk_bf16_f32 v177, v166, v167
	v_cvt_pk_bf16_f32 v178, v168, v169
	v_cvt_pk_bf16_f32 v179, v170, v171
	global_store_dwordx4 v181, v[176:179], s[18:19] offset:2048
	s_waitcnt vmcnt(15)
	v_lshlrev_b32_e32 v140, 16, v60
	v_and_b32_e32 v141, 0xffff0000, v60
	v_lshlrev_b32_e32 v142, 16, v61
	v_and_b32_e32 v143, 0xffff0000, v61
	v_lshlrev_b32_e32 v144, 16, v62
	v_and_b32_e32 v145, 0xffff0000, v62
	v_lshlrev_b32_e32 v146, 16, v63
	v_and_b32_e32 v147, 0xffff0000, v63
	v_pk_fma_f32 v[164:165], v[76:77], v[116:117], v[108:109]
	v_pk_fma_f32 v[166:167], v[78:79], v[118:119], v[110:111]
	v_pk_fma_f32 v[168:169], v[80:81], v[120:121], v[112:113]
	v_pk_fma_f32 v[170:171], v[82:83], v[122:123], v[114:115]
	v_pk_fma_f32 v[164:165], v[84:85], v[124:125], v[164:165]
	v_pk_fma_f32 v[166:167], v[86:87], v[126:127], v[166:167]
	v_pk_fma_f32 v[168:169], v[88:89], v[128:129], v[168:169]
	v_pk_fma_f32 v[170:171], v[90:91], v[130:131], v[170:171]
	v_pk_fma_f32 v[164:165], v[92:93], v[132:133], v[164:165]
	v_pk_fma_f32 v[166:167], v[94:95], v[134:135], v[166:167]
	v_pk_fma_f32 v[168:169], v[96:97], v[136:137], v[168:169]
	v_pk_fma_f32 v[170:171], v[98:99], v[138:139], v[170:171]
	v_pk_fma_f32 v[164:165], v[100:101], v[140:141], v[164:165]
	v_pk_fma_f32 v[166:167], v[102:103], v[142:143], v[166:167]
	v_pk_fma_f32 v[168:169], v[104:105], v[144:145], v[168:169]
	v_pk_fma_f32 v[170:171], v[106:107], v[146:147], v[170:171]
	v_cvt_pk_bf16_f32 v172, v164, v165
	v_cvt_pk_bf16_f32 v173, v166, v167
	v_cvt_pk_bf16_f32 v174, v168, v169
	v_cvt_pk_bf16_f32 v175, v170, v171
	s_add_u32 s18, s18, 0x2000
	s_addc_u32 s19, s19, 0
	global_store_dwordx4 v181, v[172:175], s[18:19] offset:-4096
	s_waitcnt vmcnt(15)
	v_lshlrev_b32_e32 v116, 16, v64
	v_and_b32_e32 v117, 0xffff0000, v64
	v_lshlrev_b32_e32 v118, 16, v65
	v_and_b32_e32 v119, 0xffff0000, v65
	v_lshlrev_b32_e32 v120, 16, v66
	v_and_b32_e32 v121, 0xffff0000, v66
	v_lshlrev_b32_e32 v122, 16, v67
	v_and_b32_e32 v123, 0xffff0000, v67
	v_pk_fma_f32 v[164:165], v[76:77], v[124:125], v[108:109]
	v_pk_fma_f32 v[166:167], v[78:79], v[126:127], v[110:111]
	v_pk_fma_f32 v[168:169], v[80:81], v[128:129], v[112:113]
	v_pk_fma_f32 v[170:171], v[82:83], v[130:131], v[114:115]
	v_pk_fma_f32 v[164:165], v[84:85], v[132:133], v[164:165]
	v_pk_fma_f32 v[166:167], v[86:87], v[134:135], v[166:167]
	v_pk_fma_f32 v[168:169], v[88:89], v[136:137], v[168:169]
	v_pk_fma_f32 v[170:171], v[90:91], v[138:139], v[170:171]
	v_pk_fma_f32 v[164:165], v[92:93], v[140:141], v[164:165]
	v_pk_fma_f32 v[166:167], v[94:95], v[142:143], v[166:167]
	v_pk_fma_f32 v[168:169], v[96:97], v[144:145], v[168:169]
	v_pk_fma_f32 v[170:171], v[98:99], v[146:147], v[170:171]
	v_pk_fma_f32 v[164:165], v[100:101], v[116:117], v[164:165]
	v_pk_fma_f32 v[166:167], v[102:103], v[118:119], v[166:167]
	v_pk_fma_f32 v[168:169], v[104:105], v[120:121], v[168:169]
	v_pk_fma_f32 v[170:171], v[106:107], v[122:123], v[170:171]
	v_cvt_pk_bf16_f32 v176, v164, v165
	v_cvt_pk_bf16_f32 v177, v166, v167
	v_cvt_pk_bf16_f32 v178, v168, v169
	v_cvt_pk_bf16_f32 v179, v170, v171
	global_store_dwordx4 v181, v[176:179], s[18:19] offset:-2048
	s_waitcnt vmcnt(15)
	v_lshlrev_b32_e32 v124, 16, v68
	v_and_b32_e32 v125, 0xffff0000, v68
	v_lshlrev_b32_e32 v126, 16, v69
	v_and_b32_e32 v127, 0xffff0000, v69
	v_lshlrev_b32_e32 v128, 16, v70
	v_and_b32_e32 v129, 0xffff0000, v70
	v_lshlrev_b32_e32 v130, 16, v71
	v_and_b32_e32 v131, 0xffff0000, v71
	v_pk_fma_f32 v[164:165], v[76:77], v[132:133], v[108:109]
	v_pk_fma_f32 v[166:167], v[78:79], v[134:135], v[110:111]
	v_pk_fma_f32 v[168:169], v[80:81], v[136:137], v[112:113]
	v_pk_fma_f32 v[170:171], v[82:83], v[138:139], v[114:115]
	v_pk_fma_f32 v[164:165], v[84:85], v[140:141], v[164:165]
	v_pk_fma_f32 v[166:167], v[86:87], v[142:143], v[166:167]
	v_pk_fma_f32 v[168:169], v[88:89], v[144:145], v[168:169]
	v_pk_fma_f32 v[170:171], v[90:91], v[146:147], v[170:171]
	v_pk_fma_f32 v[164:165], v[92:93], v[116:117], v[164:165]
	v_pk_fma_f32 v[166:167], v[94:95], v[118:119], v[166:167]
	v_pk_fma_f32 v[168:169], v[96:97], v[120:121], v[168:169]
	v_pk_fma_f32 v[170:171], v[98:99], v[122:123], v[170:171]
	v_pk_fma_f32 v[164:165], v[100:101], v[124:125], v[164:165]
	v_pk_fma_f32 v[166:167], v[102:103], v[126:127], v[166:167]
	v_pk_fma_f32 v[168:169], v[104:105], v[128:129], v[168:169]
	v_pk_fma_f32 v[170:171], v[106:107], v[130:131], v[170:171]
	v_cvt_pk_bf16_f32 v172, v164, v165
	v_cvt_pk_bf16_f32 v173, v166, v167
	v_cvt_pk_bf16_f32 v174, v168, v169
	v_cvt_pk_bf16_f32 v175, v170, v171
	global_store_dwordx4 v181, v[172:175], s[18:19] offset:0
	s_waitcnt vmcnt(15)
	s_cmp_eq_u32 s25, 1
	s_cbranch_scc1 .Lp3_hiok
	v_mov_b32_e32 v72, 0
	v_mov_b32_e32 v73, 0
	v_mov_b32_e32 v74, 0
	v_mov_b32_e32 v75, 0
.Lp3_hiok:
	v_lshlrev_b32_e32 v132, 16, v72
	v_and_b32_e32 v133, 0xffff0000, v72
	v_lshlrev_b32_e32 v134, 16, v73
	v_and_b32_e32 v135, 0xffff0000, v73
	v_lshlrev_b32_e32 v136, 16, v74
	v_and_b32_e32 v137, 0xffff0000, v74
	v_lshlrev_b32_e32 v138, 16, v75
	v_and_b32_e32 v139, 0xffff0000, v75
	v_pk_fma_f32 v[164:165], v[76:77], v[140:141], v[108:109]
	v_pk_fma_f32 v[166:167], v[78:79], v[142:143], v[110:111]
	v_pk_fma_f32 v[168:169], v[80:81], v[144:145], v[112:113]
	v_pk_fma_f32 v[170:171], v[82:83], v[146:147], v[114:115]
	v_pk_fma_f32 v[164:165], v[84:85], v[116:117], v[164:165]
	v_pk_fma_f32 v[166:167], v[86:87], v[118:119], v[166:167]
	v_pk_fma_f32 v[168:169], v[88:89], v[120:121], v[168:169]
	v_pk_fma_f32 v[170:171], v[90:91], v[122:123], v[170:171]
	v_pk_fma_f32 v[164:165], v[92:93], v[124:125], v[164:165]
	v_pk_fma_f32 v[166:167], v[94:95], v[126:127], v[166:167]
	v_pk_fma_f32 v[168:169], v[96:97], v[128:129], v[168:169]
	v_pk_fma_f32 v[170:171], v[98:99], v[130:131], v[170:171]
	v_pk_fma_f32 v[164:165], v[100:101], v[132:133], v[164:165]
	v_pk_fma_f32 v[166:167], v[102:103], v[134:135], v[166:167]
	v_pk_fma_f32 v[168:169], v[104:105], v[136:137], v[168:169]
	v_pk_fma_f32 v[170:171], v[106:107], v[138:139], v[170:171]
	v_cvt_pk_bf16_f32 v176, v164, v165
	v_cvt_pk_bf16_f32 v177, v166, v167
	v_cvt_pk_bf16_f32 v178, v168, v169
	v_cvt_pk_bf16_f32 v179, v170, v171
	global_store_dwordx4 v181, v[176:179], s[18:19] offset:2048
	s_add_u32 s2, s2, s3
	s_cmp_lt_u32 s2, 0x42000
	s_cbranch_scc1 .Lp3_item
